# NA: per-tile rescale branch test shortened (s_or into vcc + s_cbranch_vccz, one SALU op fewer on the serial chain)
# speedup vs baseline: 1.0039x; 1.0039x over previous
.Lna_wloop:
	s_sub_i32 s36, s24, s23
	s_cmp_lt_u32 s36, s63
	s_cselect_b64 s[40:41], -1, 0
	s_add_i32 s36, s36, 1
	s_cmp_lt_u32 s36, 8
	s_cselect_b64 s[44:45], -1, 0
	s_sub_i32 s37, s36, s62
	s_cmp_lt_u32 s37, 8
	s_cselect_b64 s[46:47], -1, 0
	s_and_b64 s[48:49], s[44:45], s[64:65]
	s_andn2_b64 s[38:39], s[46:47], s[64:65]
	s_or_b64 s[48:49], s[48:49], s[38:39]
	s_or_b64 s[42:43], s[44:45], s[46:47]
	s_and_b64 s[44:45], s[44:45], s[46:47]
	s_and_b64 s[44:45], s[44:45], s[40:41]
	s_cmp_eq_u64 s[44:45], 0
	s_cbranch_scc1 .Lna_slow_w1
	ds_read_b128 v[146:149], v199 offset:0
	ds_read_b128 v[150:153], v199 offset:32
	ds_read_b128 v[154:157], v199 offset:64
	ds_read_b128 v[158:161], v199 offset:96
	v_add_u32_e32 v210, s25, v208
	v_exp_f32_e32 v66, v66
	v_exp_f32_e32 v67, v67
	v_exp_f32_e32 v68, v68
	v_exp_f32_e32 v69, v69
	v_add_f32_e32 v213, v213, v66
	v_add_f32_e32 v214, v214, v67
	s_waitcnt lgkmcnt(3)
	v_mfma_f32_32x32x16_bf16 v[34:49], v[146:149], v[98:101], v[114:129]
	ds_read_b64 v[162:163], v201 offset:8704
	ds_read_b64 v[164:165], v201 offset:8720
	v_add_f32_e32 v213, v213, v68
	v_add_f32_e32 v214, v214, v69
	v_exp_f32_e32 v70, v70
	v_exp_f32_e32 v71, v71
	v_exp_f32_e32 v72, v72
	v_exp_f32_e32 v73, v73
	s_waitcnt lgkmcnt(4)
	v_mfma_f32_32x32x16_bf16 v[34:49], v[150:153], v[102:105], v[34:49]
	ds_read_b64 v[166:167], v201 offset:13056
	ds_read_b64 v[168:169], v201 offset:13072
	v_add_f32_e32 v213, v213, v70
	v_add_f32_e32 v214, v214, v71
	v_add_f32_e32 v213, v213, v72
	v_add_f32_e32 v214, v214, v73
	v_cvt_pk_bf16_f32 v66, v66, v67
	v_cvt_pk_bf16_f32 v67, v68, v69
	v_cvt_pk_bf16_f32 v68, v70, v71
	v_cvt_pk_bf16_f32 v69, v72, v73
	s_waitcnt lgkmcnt(5)
	v_mfma_f32_32x32x16_bf16 v[34:49], v[154:157], v[106:109], v[34:49]
	ds_read_b64 v[170:171], v201 offset:8736
	ds_read_b64 v[172:173], v201 offset:8752
	v_exp_f32_e32 v74, v74
	v_exp_f32_e32 v75, v75
	v_exp_f32_e32 v76, v76
	v_exp_f32_e32 v77, v77
	v_add_f32_e32 v213, v213, v74
	s_waitcnt lgkmcnt(6)
	v_mfma_f32_32x32x16_bf16 v[34:49], v[158:161], v[110:113], v[34:49]
	ds_read_b64 v[174:175], v201 offset:13088
	ds_read_b64 v[176:177], v201 offset:13104
	ds_read_b128 v[146:149], v210 offset:0
	ds_read_b128 v[150:153], v210 offset:32
	ds_read_b128 v[154:157], v210 offset:64
	ds_read_b128 v[158:161], v210 offset:96
	v_add_f32_e32 v214, v214, v75
	v_add_f32_e32 v213, v213, v76
	v_add_f32_e32 v214, v214, v77
	v_exp_f32_e32 v78, v78
	v_exp_f32_e32 v79, v79
	v_exp_f32_e32 v80, v80
	s_waitcnt lgkmcnt(10)
	v_mfma_f32_32x32x16_bf16 v[2:17], v[162:165], v[66:69], v[2:17]
	v_exp_f32_e32 v81, v81
	v_add_f32_e32 v213, v213, v78
	v_add_f32_e32 v214, v214, v79
	v_add_f32_e32 v213, v213, v80
	v_add_f32_e32 v214, v214, v81
	v_cvt_pk_bf16_f32 v74, v74, v75
	v_cvt_pk_bf16_f32 v75, v76, v77
	v_cvt_pk_bf16_f32 v76, v78, v79
	s_waitcnt lgkmcnt(8)
	v_mfma_f32_32x32x16_bf16 v[18:33], v[166:169], v[66:69], v[18:33]
	v_cvt_pk_bf16_f32 v77, v80, v81
	s_waitcnt lgkmcnt(0)
	v_add_f32_e32 v34, v34, v146
	v_add_f32_e32 v35, v35, v147
	v_add_f32_e32 v36, v36, v148
	v_add_f32_e32 v37, v37, v149
	v_add_f32_e32 v38, v38, v150
	v_add_f32_e32 v39, v39, v151
	v_add_f32_e32 v40, v40, v152
	v_add_f32_e32 v41, v41, v153
	v_mfma_f32_32x32x16_bf16 v[2:17], v[170:173], v[74:77], v[2:17]
	v_add_f32_e32 v42, v42, v154
	v_add_f32_e32 v43, v43, v155
	v_add_f32_e32 v44, v44, v156
	v_add_f32_e32 v45, v45, v157
	v_add_f32_e32 v46, v46, v158
	v_add_f32_e32 v47, v47, v159
	v_add_f32_e32 v48, v48, v160
	v_add_f32_e32 v49, v49, v161
	v_max3_f32 v216, v34, v35, v36
	v_mfma_f32_32x32x16_bf16 v[18:33], v[174:177], v[74:77], v[18:33]
	s_waitcnt vmcnt(2)
	ds_write_b128 v204, v[230:233] offset:9216
	ds_write_b64 v205, v[234:235] offset:0
	ds_write_b64 v205, v[236:237] offset:8
	global_load_dwordx4 v[230:233], v206, s[12:13]
	s_add_i32 s20, s20, 1
	s_add_u32 s12, s12, 0x2000
	s_addc_u32 s13, s13, 0
	s_cmp_eq_u32 s20, s22
	s_cselect_b32 s12, s16, s12
	s_cselect_b32 s13, s17, s13
	global_load_dwordx4 v[234:237], v207, s[14:15]
	s_add_i32 s21, s21, 1
	s_add_u32 s14, s14, 0x80
	s_addc_u32 s15, s15, 0
	s_cmp_eq_u32 s21, s22
	s_cselect_b32 s14, s18, s14
	s_cselect_b32 s15, s19, s15
	v_max3_f32 v217, v42, v43, v44
	v_max3_f32 v216, v216, v37, v38
	v_max3_f32 v217, v217, v45, v46
	v_max3_f32 v216, v216, v39, v40
	v_max3_f32 v217, v217, v47, v48
	v_max_f32_e32 v216, v216, v41
	v_max_f32_e32 v217, v217, v49
	v_max_f32_e32 v216, v216, v217
	v_cmp_lt_f32_e32 vcc, 4.0, v216
	s_or_b64 vcc, vcc, s[26:27]
	s_cbranch_vccz .Lna_nr_w1f
	v_mov_b32_e32 v217, v216
	s_nop 1
	v_permlane32_swap_b32_e32 v216, v217
	v_max_f32_e32 v215, v216, v217
	s_nop 15
	v_max_f32_e32 v216, v215, v220
	v_cmp_lt_f32_e32 vcc, 0xf0c9f2ca, v215
	s_nop 1
	v_cndmask_b32_e32 v216, 0, v216, vcc
	v_exp_f32_e64 v217, -v216
	v_add_f32_e32 v212, v212, v216
	v_and_b32_e32 v217, v217, v221
	v_sub_f32_e32 v34, v34, v216
	v_sub_f32_e32 v35, v35, v216
	v_sub_f32_e32 v36, v36, v216
	v_sub_f32_e32 v37, v37, v216
	v_sub_f32_e32 v38, v38, v216
	v_sub_f32_e32 v39, v39, v216
	v_sub_f32_e32 v40, v40, v216
	v_sub_f32_e32 v41, v41, v216
	v_sub_f32_e32 v42, v42, v216
	v_sub_f32_e32 v43, v43, v216
	v_sub_f32_e32 v44, v44, v216
	v_sub_f32_e32 v45, v45, v216
	v_sub_f32_e32 v46, v46, v216
	v_sub_f32_e32 v47, v47, v216
	v_sub_f32_e32 v48, v48, v216
	v_sub_f32_e32 v49, v49, v216
	v_sub_f32_e32 v114, v114, v216
	v_sub_f32_e32 v115, v115, v216
	v_sub_f32_e32 v116, v116, v216
	v_sub_f32_e32 v117, v117, v216
	v_sub_f32_e32 v118, v118, v216
	v_sub_f32_e32 v119, v119, v216
	v_sub_f32_e32 v120, v120, v216
	v_sub_f32_e32 v121, v121, v216
	v_sub_f32_e32 v122, v122, v216
	v_sub_f32_e32 v123, v123, v216
	v_sub_f32_e32 v124, v124, v216
	v_sub_f32_e32 v125, v125, v216
	v_sub_f32_e32 v126, v126, v216
	v_sub_f32_e32 v127, v127, v216
	v_sub_f32_e32 v128, v128, v216
	v_sub_f32_e32 v129, v129, v216
	v_mul_f32_e32 v213, v213, v217
	v_mul_f32_e32 v214, v214, v217
	v_mul_f32_e32 v2, v2, v217
	v_mul_f32_e32 v3, v3, v217
	v_mul_f32_e32 v4, v4, v217
	v_mul_f32_e32 v5, v5, v217
	v_mul_f32_e32 v6, v6, v217
	v_mul_f32_e32 v7, v7, v217
	v_mul_f32_e32 v8, v8, v217
	v_mul_f32_e32 v9, v9, v217
	v_mul_f32_e32 v10, v10, v217
	v_mul_f32_e32 v11, v11, v217
	v_mul_f32_e32 v12, v12, v217
	v_mul_f32_e32 v13, v13, v217
	v_mul_f32_e32 v14, v14, v217
	v_mul_f32_e32 v15, v15, v217
	v_mul_f32_e32 v16, v16, v217
	v_mul_f32_e32 v17, v17, v217
	v_mul_f32_e32 v18, v18, v217
	v_mul_f32_e32 v19, v19, v217
	v_mul_f32_e32 v20, v20, v217
	v_mul_f32_e32 v21, v21, v217
	v_mul_f32_e32 v22, v22, v217
	v_mul_f32_e32 v23, v23, v217
	v_mul_f32_e32 v24, v24, v217
	v_mul_f32_e32 v25, v25, v217
	v_mul_f32_e32 v26, v26, v217
	v_mul_f32_e32 v27, v27, v217
	v_mul_f32_e32 v28, v28, v217
	v_mul_f32_e32 v29, v29, v217
	v_mul_f32_e32 v30, v30, v217
	v_mul_f32_e32 v31, v31, v217
	v_mul_f32_e32 v32, v32, v217
	v_mul_f32_e32 v33, v33, v217
	v_cndmask_b32_e32 v220, v220, v228, vcc
	v_cndmask_b32_e64 v221, v221, -1, vcc
	s_andn2_b64 s[26:27], s[26:27], vcc

.Lna_sl_a_w1s:
	s_waitcnt lgkmcnt(0)
	s_cmp_eq_u64 s[42:43], 0
	s_cbranch_scc1 .Lna_sl_b_w1s
	ds_read_b128 v[146:149], v199 offset:0
	ds_read_b128 v[150:153], v199 offset:32
	ds_read_b128 v[154:157], v199 offset:64
	ds_read_b128 v[158:161], v199 offset:96
	s_waitcnt lgkmcnt(3)
	v_mfma_f32_32x32x16_bf16 v[34:49], v[146:149], v[98:101], v[114:129]
	s_waitcnt lgkmcnt(2)
	v_mfma_f32_32x32x16_bf16 v[34:49], v[150:153], v[102:105], v[34:49]
	s_waitcnt lgkmcnt(1)
	v_mfma_f32_32x32x16_bf16 v[34:49], v[154:157], v[106:109], v[34:49]
	s_waitcnt lgkmcnt(0)
	v_mfma_f32_32x32x16_bf16 v[34:49], v[158:161], v[110:113], v[34:49]
	v_add_u32_e32 v210, s25, v208
	ds_read_b128 v[146:149], v210 offset:0
	ds_read_b128 v[150:153], v210 offset:32
	ds_read_b128 v[154:157], v210 offset:64
	ds_read_b128 v[158:161], v210 offset:96
	s_waitcnt lgkmcnt(0)
	s_nop 15
	v_add_f32_e32 v34, v34, v146
	v_add_f32_e32 v35, v35, v147
	v_add_f32_e32 v36, v36, v148
	v_add_f32_e32 v37, v37, v149
	v_add_f32_e32 v38, v38, v150
	v_add_f32_e32 v39, v39, v151
	v_add_f32_e32 v40, v40, v152
	v_add_f32_e32 v41, v41, v153
	v_add_f32_e32 v42, v42, v154
	v_add_f32_e32 v43, v43, v155
	v_add_f32_e32 v44, v44, v156
	v_add_f32_e32 v45, v45, v157
	v_add_f32_e32 v46, v46, v158
	v_add_f32_e32 v47, v47, v159
	v_add_f32_e32 v48, v48, v160
	v_add_f32_e32 v49, v49, v161
	v_cndmask_b32_e64 v34, v229, v34, s[48:49]
	v_cndmask_b32_e64 v35, v229, v35, s[48:49]
	v_cndmask_b32_e64 v36, v229, v36, s[48:49]
	v_cndmask_b32_e64 v37, v229, v37, s[48:49]
	v_cndmask_b32_e64 v38, v229, v38, s[48:49]
	v_cndmask_b32_e64 v39, v229, v39, s[48:49]
	v_cndmask_b32_e64 v40, v229, v40, s[48:49]
	v_cndmask_b32_e64 v41, v229, v41, s[48:49]
	v_cndmask_b32_e64 v42, v229, v42, s[48:49]
	v_cndmask_b32_e64 v43, v229, v43, s[48:49]
	v_cndmask_b32_e64 v44, v229, v44, s[48:49]
	v_cndmask_b32_e64 v45, v229, v45, s[48:49]
	v_cndmask_b32_e64 v46, v229, v46, s[48:49]
	v_cndmask_b32_e64 v47, v229, v47, s[48:49]
	v_cndmask_b32_e64 v48, v229, v48, s[48:49]
	v_cndmask_b32_e64 v49, v229, v49, s[48:49]
	v_max3_f32 v216, v34, v35, v36
	v_max3_f32 v217, v42, v43, v44
	v_max3_f32 v216, v216, v37, v38
	v_max3_f32 v217, v217, v45, v46
	v_max3_f32 v216, v216, v39, v40
	v_max3_f32 v217, v217, v47, v48
	v_max_f32_e32 v216, v216, v41
	v_max_f32_e32 v217, v217, v49
	v_max_f32_e32 v216, v216, v217
	v_cmp_lt_f32_e32 vcc, 4.0, v216
	s_or_b64 vcc, vcc, s[26:27]
	s_cbranch_vccz .Lna_nr_w1s
	v_mov_b32_e32 v217, v216
	s_nop 1
	v_permlane32_swap_b32_e32 v216, v217
	v_max_f32_e32 v215, v216, v217
	s_nop 15
	v_max_f32_e32 v216, v215, v220
	v_cmp_lt_f32_e32 vcc, 0xf0c9f2ca, v215
	s_nop 1
	v_cndmask_b32_e32 v216, 0, v216, vcc
	v_exp_f32_e64 v217, -v216
	v_add_f32_e32 v212, v212, v216
	v_and_b32_e32 v217, v217, v221
	v_sub_f32_e32 v34, v34, v216
	v_sub_f32_e32 v35, v35, v216
	v_sub_f32_e32 v36, v36, v216
	v_sub_f32_e32 v37, v37, v216
	v_sub_f32_e32 v38, v38, v216
	v_sub_f32_e32 v39, v39, v216
	v_sub_f32_e32 v40, v40, v216
	v_sub_f32_e32 v41, v41, v216
	v_sub_f32_e32 v42, v42, v216
	v_sub_f32_e32 v43, v43, v216
	v_sub_f32_e32 v44, v44, v216
	v_sub_f32_e32 v45, v45, v216
	v_sub_f32_e32 v46, v46, v216
	v_sub_f32_e32 v47, v47, v216
	v_sub_f32_e32 v48, v48, v216
	v_sub_f32_e32 v49, v49, v216
	v_sub_f32_e32 v114, v114, v216
	v_sub_f32_e32 v115, v115, v216
	v_sub_f32_e32 v116, v116, v216
	v_sub_f32_e32 v117, v117, v216
	v_sub_f32_e32 v118, v118, v216
	v_sub_f32_e32 v119, v119, v216
	v_sub_f32_e32 v120, v120, v216
	v_sub_f32_e32 v121, v121, v216
	v_sub_f32_e32 v122, v122, v216
	v_sub_f32_e32 v123, v123, v216
	v_sub_f32_e32 v124, v124, v216
	v_sub_f32_e32 v125, v125, v216
	v_sub_f32_e32 v126, v126, v216
	v_sub_f32_e32 v127, v127, v216
	v_sub_f32_e32 v128, v128, v216
	v_sub_f32_e32 v129, v129, v216
	v_mul_f32_e32 v213, v213, v217
	v_mul_f32_e32 v214, v214, v217
	v_mul_f32_e32 v2, v2, v217
	v_mul_f32_e32 v3, v3, v217
	v_mul_f32_e32 v4, v4, v217
	v_mul_f32_e32 v5, v5, v217
	v_mul_f32_e32 v6, v6, v217
	v_mul_f32_e32 v7, v7, v217
	v_mul_f32_e32 v8, v8, v217
	v_mul_f32_e32 v9, v9, v217
	v_mul_f32_e32 v10, v10, v217
	v_mul_f32_e32 v11, v11, v217
	v_mul_f32_e32 v12, v12, v217
	v_mul_f32_e32 v13, v13, v217
	v_mul_f32_e32 v14, v14, v217
	v_mul_f32_e32 v15, v15, v217
	v_mul_f32_e32 v16, v16, v217
	v_mul_f32_e32 v17, v17, v217
	v_mul_f32_e32 v18, v18, v217
	v_mul_f32_e32 v19, v19, v217
	v_mul_f32_e32 v20, v20, v217
	v_mul_f32_e32 v21, v21, v217
	v_mul_f32_e32 v22, v22, v217
	v_mul_f32_e32 v23, v23, v217
	v_mul_f32_e32 v24, v24, v217
	v_mul_f32_e32 v25, v25, v217
	v_mul_f32_e32 v26, v26, v217
	v_mul_f32_e32 v27, v27, v217
	v_mul_f32_e32 v28, v28, v217
	v_mul_f32_e32 v29, v29, v217
	v_mul_f32_e32 v30, v30, v217
	v_mul_f32_e32 v31, v31, v217
	v_mul_f32_e32 v32, v32, v217
	v_mul_f32_e32 v33, v33, v217
	v_cndmask_b32_e32 v220, v220, v228, vcc
	v_cndmask_b32_e64 v221, v221, -1, vcc
	s_andn2_b64 s[26:27], s[26:27], vcc

.Lna_done_w1:
	s_add_i32 s24, s24, 1
	s_add_i32 s25, s25, 0x150
	s_sub_i32 s36, s24, s23
	s_cmp_lt_u32 s36, s63
	s_cselect_b64 s[40:41], -1, 0
	s_add_i32 s36, s36, 1
	s_cmp_lt_u32 s36, 8
	s_cselect_b64 s[44:45], -1, 0
	s_sub_i32 s37, s36, s62
	s_cmp_lt_u32 s37, 8
	s_cselect_b64 s[46:47], -1, 0
	s_and_b64 s[48:49], s[44:45], s[64:65]
	s_andn2_b64 s[38:39], s[46:47], s[64:65]
	s_or_b64 s[48:49], s[48:49], s[38:39]
	s_or_b64 s[42:43], s[44:45], s[46:47]
	s_and_b64 s[44:45], s[44:45], s[46:47]
	s_and_b64 s[44:45], s[44:45], s[40:41]
	s_cmp_eq_u64 s[44:45], 0
	s_cbranch_scc1 .Lna_slow_w0
	ds_read_b128 v[146:149], v199 offset:9216
	ds_read_b128 v[150:153], v199 offset:9248
	ds_read_b128 v[154:157], v199 offset:9280
	ds_read_b128 v[158:161], v199 offset:9312
	v_add_u32_e32 v210, s25, v208
	v_exp_f32_e32 v34, v34
	v_exp_f32_e32 v35, v35
	v_exp_f32_e32 v36, v36
	v_exp_f32_e32 v37, v37
	v_add_f32_e32 v213, v213, v34
	v_add_f32_e32 v214, v214, v35
	s_waitcnt lgkmcnt(3)
	v_mfma_f32_32x32x16_bf16 v[66:81], v[146:149], v[98:101], v[114:129]
	ds_read_b64 v[162:163], v201 offset:0
	ds_read_b64 v[164:165], v201 offset:16
	v_add_f32_e32 v213, v213, v36
	v_add_f32_e32 v214, v214, v37
	v_exp_f32_e32 v38, v38
	v_exp_f32_e32 v39, v39
	v_exp_f32_e32 v40, v40
	v_exp_f32_e32 v41, v41
	s_waitcnt lgkmcnt(4)
	v_mfma_f32_32x32x16_bf16 v[66:81], v[150:153], v[102:105], v[66:81]
	ds_read_b64 v[166:167], v201 offset:4352
	ds_read_b64 v[168:169], v201 offset:4368
	v_add_f32_e32 v213, v213, v38
	v_add_f32_e32 v214, v214, v39
	v_add_f32_e32 v213, v213, v40
	v_add_f32_e32 v214, v214, v41
	v_cvt_pk_bf16_f32 v34, v34, v35
	v_cvt_pk_bf16_f32 v35, v36, v37
	v_cvt_pk_bf16_f32 v36, v38, v39
	v_cvt_pk_bf16_f32 v37, v40, v41
	s_waitcnt lgkmcnt(5)
	v_mfma_f32_32x32x16_bf16 v[66:81], v[154:157], v[106:109], v[66:81]
	ds_read_b64 v[170:171], v201 offset:32
	ds_read_b64 v[172:173], v201 offset:48
	v_exp_f32_e32 v42, v42
	v_exp_f32_e32 v43, v43
	v_exp_f32_e32 v44, v44
	v_exp_f32_e32 v45, v45
	v_add_f32_e32 v213, v213, v42
	s_waitcnt lgkmcnt(6)
	v_mfma_f32_32x32x16_bf16 v[66:81], v[158:161], v[110:113], v[66:81]
	ds_read_b64 v[174:175], v201 offset:4384
	ds_read_b64 v[176:177], v201 offset:4400
	ds_read_b128 v[146:149], v210 offset:0
	ds_read_b128 v[150:153], v210 offset:32
	ds_read_b128 v[154:157], v210 offset:64
	ds_read_b128 v[158:161], v210 offset:96
	v_add_f32_e32 v214, v214, v43
	v_add_f32_e32 v213, v213, v44
	v_add_f32_e32 v214, v214, v45
	v_exp_f32_e32 v46, v46
	v_exp_f32_e32 v47, v47
	v_exp_f32_e32 v48, v48
	s_waitcnt lgkmcnt(10)
	v_mfma_f32_32x32x16_bf16 v[2:17], v[162:165], v[34:37], v[2:17]
	v_exp_f32_e32 v49, v49
	v_add_f32_e32 v213, v213, v46
	v_add_f32_e32 v214, v214, v47
	v_add_f32_e32 v213, v213, v48
	v_add_f32_e32 v214, v214, v49
	v_cvt_pk_bf16_f32 v42, v42, v43
	v_cvt_pk_bf16_f32 v43, v44, v45
	v_cvt_pk_bf16_f32 v44, v46, v47
	s_waitcnt lgkmcnt(8)
	v_mfma_f32_32x32x16_bf16 v[18:33], v[166:169], v[34:37], v[18:33]
	v_cvt_pk_bf16_f32 v45, v48, v49
	s_waitcnt lgkmcnt(0)
	v_add_f32_e32 v66, v66, v146
	v_add_f32_e32 v67, v67, v147
	v_add_f32_e32 v68, v68, v148
	v_add_f32_e32 v69, v69, v149
	v_add_f32_e32 v70, v70, v150
	v_add_f32_e32 v71, v71, v151
	v_add_f32_e32 v72, v72, v152
	v_add_f32_e32 v73, v73, v153
	v_mfma_f32_32x32x16_bf16 v[2:17], v[170:173], v[42:45], v[2:17]
	v_add_f32_e32 v74, v74, v154
	v_add_f32_e32 v75, v75, v155
	v_add_f32_e32 v76, v76, v156
	v_add_f32_e32 v77, v77, v157
	v_add_f32_e32 v78, v78, v158
	v_add_f32_e32 v79, v79, v159
	v_add_f32_e32 v80, v80, v160
	v_add_f32_e32 v81, v81, v161
	v_max3_f32 v216, v66, v67, v68
	v_mfma_f32_32x32x16_bf16 v[18:33], v[174:177], v[42:45], v[18:33]
	s_waitcnt vmcnt(2)
	ds_write_b128 v204, v[188:191] offset:0
	ds_write_b64 v205, v[192:193] offset:8704
	ds_write_b64 v205, v[194:195] offset:8712
	global_load_dwordx4 v[188:191], v206, s[12:13]
	s_add_i32 s20, s20, 1
	s_add_u32 s12, s12, 0x2000
	s_addc_u32 s13, s13, 0
	s_cmp_eq_u32 s20, s22
	s_cselect_b32 s12, s16, s12
	s_cselect_b32 s13, s17, s13
	global_load_dwordx4 v[192:195], v207, s[14:15]
	s_add_i32 s21, s21, 1
	s_add_u32 s14, s14, 0x80
	s_addc_u32 s15, s15, 0
	s_cmp_eq_u32 s21, s22
	s_cselect_b32 s14, s18, s14
	s_cselect_b32 s15, s19, s15
	v_max3_f32 v217, v74, v75, v76
	v_max3_f32 v216, v216, v69, v70
	v_max3_f32 v217, v217, v77, v78
	v_max3_f32 v216, v216, v71, v72
	v_max3_f32 v217, v217, v79, v80
	v_max_f32_e32 v216, v216, v73
	v_max_f32_e32 v217, v217, v81
	v_max_f32_e32 v216, v216, v217
	v_cmp_lt_f32_e32 vcc, 4.0, v216
	s_or_b64 vcc, vcc, s[26:27]
	s_cbranch_vccz .Lna_nr_w0f
	v_mov_b32_e32 v217, v216
	s_nop 1
	v_permlane32_swap_b32_e32 v216, v217
	v_max_f32_e32 v215, v216, v217
	s_nop 15
	v_max_f32_e32 v216, v215, v220
	v_cmp_lt_f32_e32 vcc, 0xf0c9f2ca, v215
	s_nop 1
	v_cndmask_b32_e32 v216, 0, v216, vcc
	v_exp_f32_e64 v217, -v216
	v_add_f32_e32 v212, v212, v216
	v_and_b32_e32 v217, v217, v221
	v_sub_f32_e32 v66, v66, v216
	v_sub_f32_e32 v67, v67, v216
	v_sub_f32_e32 v68, v68, v216
	v_sub_f32_e32 v69, v69, v216
	v_sub_f32_e32 v70, v70, v216
	v_sub_f32_e32 v71, v71, v216
	v_sub_f32_e32 v72, v72, v216
	v_sub_f32_e32 v73, v73, v216
	v_sub_f32_e32 v74, v74, v216
	v_sub_f32_e32 v75, v75, v216
	v_sub_f32_e32 v76, v76, v216
	v_sub_f32_e32 v77, v77, v216
	v_sub_f32_e32 v78, v78, v216
	v_sub_f32_e32 v79, v79, v216
	v_sub_f32_e32 v80, v80, v216
	v_sub_f32_e32 v81, v81, v216
	v_sub_f32_e32 v114, v114, v216
	v_sub_f32_e32 v115, v115, v216
	v_sub_f32_e32 v116, v116, v216
	v_sub_f32_e32 v117, v117, v216
	v_sub_f32_e32 v118, v118, v216
	v_sub_f32_e32 v119, v119, v216
	v_sub_f32_e32 v120, v120, v216
	v_sub_f32_e32 v121, v121, v216
	v_sub_f32_e32 v122, v122, v216
	v_sub_f32_e32 v123, v123, v216
	v_sub_f32_e32 v124, v124, v216
	v_sub_f32_e32 v125, v125, v216
	v_sub_f32_e32 v126, v126, v216
	v_sub_f32_e32 v127, v127, v216
	v_sub_f32_e32 v128, v128, v216
	v_sub_f32_e32 v129, v129, v216
	v_mul_f32_e32 v213, v213, v217
	v_mul_f32_e32 v214, v214, v217
	v_mul_f32_e32 v2, v2, v217
	v_mul_f32_e32 v3, v3, v217
	v_mul_f32_e32 v4, v4, v217
	v_mul_f32_e32 v5, v5, v217
	v_mul_f32_e32 v6, v6, v217
	v_mul_f32_e32 v7, v7, v217
	v_mul_f32_e32 v8, v8, v217
	v_mul_f32_e32 v9, v9, v217
	v_mul_f32_e32 v10, v10, v217
	v_mul_f32_e32 v11, v11, v217
	v_mul_f32_e32 v12, v12, v217
	v_mul_f32_e32 v13, v13, v217
	v_mul_f32_e32 v14, v14, v217
	v_mul_f32_e32 v15, v15, v217
	v_mul_f32_e32 v16, v16, v217
	v_mul_f32_e32 v17, v17, v217
	v_mul_f32_e32 v18, v18, v217
	v_mul_f32_e32 v19, v19, v217
	v_mul_f32_e32 v20, v20, v217
	v_mul_f32_e32 v21, v21, v217
	v_mul_f32_e32 v22, v22, v217
	v_mul_f32_e32 v23, v23, v217
	v_mul_f32_e32 v24, v24, v217
	v_mul_f32_e32 v25, v25, v217
	v_mul_f32_e32 v26, v26, v217
	v_mul_f32_e32 v27, v27, v217
	v_mul_f32_e32 v28, v28, v217
	v_mul_f32_e32 v29, v29, v217
	v_mul_f32_e32 v30, v30, v217
	v_mul_f32_e32 v31, v31, v217
	v_mul_f32_e32 v32, v32, v217
	v_mul_f32_e32 v33, v33, v217
	v_cndmask_b32_e32 v220, v220, v228, vcc
	v_cndmask_b32_e64 v221, v221, -1, vcc
	s_andn2_b64 s[26:27], s[26:27], vcc

.Lna_sl_a_w0s:
	s_waitcnt lgkmcnt(0)
	s_cmp_eq_u64 s[42:43], 0
	s_cbranch_scc1 .Lna_sl_b_w0s
	ds_read_b128 v[146:149], v199 offset:9216
	ds_read_b128 v[150:153], v199 offset:9248
	ds_read_b128 v[154:157], v199 offset:9280
	ds_read_b128 v[158:161], v199 offset:9312
	s_waitcnt lgkmcnt(3)
	v_mfma_f32_32x32x16_bf16 v[66:81], v[146:149], v[98:101], v[114:129]
	s_waitcnt lgkmcnt(2)
	v_mfma_f32_32x32x16_bf16 v[66:81], v[150:153], v[102:105], v[66:81]
	s_waitcnt lgkmcnt(1)
	v_mfma_f32_32x32x16_bf16 v[66:81], v[154:157], v[106:109], v[66:81]
	s_waitcnt lgkmcnt(0)
	v_mfma_f32_32x32x16_bf16 v[66:81], v[158:161], v[110:113], v[66:81]
	v_add_u32_e32 v210, s25, v208
	ds_read_b128 v[146:149], v210 offset:0
	ds_read_b128 v[150:153], v210 offset:32
	ds_read_b128 v[154:157], v210 offset:64
	ds_read_b128 v[158:161], v210 offset:96
	s_waitcnt lgkmcnt(0)
	s_nop 15
	v_add_f32_e32 v66, v66, v146
	v_add_f32_e32 v67, v67, v147
	v_add_f32_e32 v68, v68, v148
	v_add_f32_e32 v69, v69, v149
	v_add_f32_e32 v70, v70, v150
	v_add_f32_e32 v71, v71, v151
	v_add_f32_e32 v72, v72, v152
	v_add_f32_e32 v73, v73, v153
	v_add_f32_e32 v74, v74, v154
	v_add_f32_e32 v75, v75, v155
	v_add_f32_e32 v76, v76, v156
	v_add_f32_e32 v77, v77, v157
	v_add_f32_e32 v78, v78, v158
	v_add_f32_e32 v79, v79, v159
	v_add_f32_e32 v80, v80, v160
	v_add_f32_e32 v81, v81, v161
	v_cndmask_b32_e64 v66, v229, v66, s[48:49]
	v_cndmask_b32_e64 v67, v229, v67, s[48:49]
	v_cndmask_b32_e64 v68, v229, v68, s[48:49]
	v_cndmask_b32_e64 v69, v229, v69, s[48:49]
	v_cndmask_b32_e64 v70, v229, v70, s[48:49]
	v_cndmask_b32_e64 v71, v229, v71, s[48:49]
	v_cndmask_b32_e64 v72, v229, v72, s[48:49]
	v_cndmask_b32_e64 v73, v229, v73, s[48:49]
	v_cndmask_b32_e64 v74, v229, v74, s[48:49]
	v_cndmask_b32_e64 v75, v229, v75, s[48:49]
	v_cndmask_b32_e64 v76, v229, v76, s[48:49]
	v_cndmask_b32_e64 v77, v229, v77, s[48:49]
	v_cndmask_b32_e64 v78, v229, v78, s[48:49]
	v_cndmask_b32_e64 v79, v229, v79, s[48:49]
	v_cndmask_b32_e64 v80, v229, v80, s[48:49]
	v_cndmask_b32_e64 v81, v229, v81, s[48:49]
	v_max3_f32 v216, v66, v67, v68
	v_max3_f32 v217, v74, v75, v76
	v_max3_f32 v216, v216, v69, v70
	v_max3_f32 v217, v217, v77, v78
	v_max3_f32 v216, v216, v71, v72
	v_max3_f32 v217, v217, v79, v80
	v_max_f32_e32 v216, v216, v73
	v_max_f32_e32 v217, v217, v81
	v_max_f32_e32 v216, v216, v217
	v_cmp_lt_f32_e32 vcc, 4.0, v216
	s_or_b64 vcc, vcc, s[26:27]
	s_cbranch_vccz .Lna_nr_w0s
	v_mov_b32_e32 v217, v216
	s_nop 1
	v_permlane32_swap_b32_e32 v216, v217
	v_max_f32_e32 v215, v216, v217
	s_nop 15
	v_max_f32_e32 v216, v215, v220
	v_cmp_lt_f32_e32 vcc, 0xf0c9f2ca, v215
	s_nop 1
	v_cndmask_b32_e32 v216, 0, v216, vcc
	v_exp_f32_e64 v217, -v216
	v_add_f32_e32 v212, v212, v216
	v_and_b32_e32 v217, v217, v221
	v_sub_f32_e32 v66, v66, v216
	v_sub_f32_e32 v67, v67, v216
	v_sub_f32_e32 v68, v68, v216
	v_sub_f32_e32 v69, v69, v216
	v_sub_f32_e32 v70, v70, v216
	v_sub_f32_e32 v71, v71, v216
	v_sub_f32_e32 v72, v72, v216
	v_sub_f32_e32 v73, v73, v216
	v_sub_f32_e32 v74, v74, v216
	v_sub_f32_e32 v75, v75, v216
	v_sub_f32_e32 v76, v76, v216
	v_sub_f32_e32 v77, v77, v216
	v_sub_f32_e32 v78, v78, v216
	v_sub_f32_e32 v79, v79, v216
	v_sub_f32_e32 v80, v80, v216
	v_sub_f32_e32 v81, v81, v216
	v_sub_f32_e32 v114, v114, v216
	v_sub_f32_e32 v115, v115, v216
	v_sub_f32_e32 v116, v116, v216
	v_sub_f32_e32 v117, v117, v216
	v_sub_f32_e32 v118, v118, v216
	v_sub_f32_e32 v119, v119, v216
	v_sub_f32_e32 v120, v120, v216
	v_sub_f32_e32 v121, v121, v216
	v_sub_f32_e32 v122, v122, v216
	v_sub_f32_e32 v123, v123, v216
	v_sub_f32_e32 v124, v124, v216
	v_sub_f32_e32 v125, v125, v216
	v_sub_f32_e32 v126, v126, v216
	v_sub_f32_e32 v127, v127, v216
	v_sub_f32_e32 v128, v128, v216
	v_sub_f32_e32 v129, v129, v216
	v_mul_f32_e32 v213, v213, v217
	v_mul_f32_e32 v214, v214, v217
	v_mul_f32_e32 v2, v2, v217
	v_mul_f32_e32 v3, v3, v217
	v_mul_f32_e32 v4, v4, v217
	v_mul_f32_e32 v5, v5, v217
	v_mul_f32_e32 v6, v6, v217
	v_mul_f32_e32 v7, v7, v217
	v_mul_f32_e32 v8, v8, v217
	v_mul_f32_e32 v9, v9, v217
	v_mul_f32_e32 v10, v10, v217
	v_mul_f32_e32 v11, v11, v217
	v_mul_f32_e32 v12, v12, v217
	v_mul_f32_e32 v13, v13, v217
	v_mul_f32_e32 v14, v14, v217
	v_mul_f32_e32 v15, v15, v217
	v_mul_f32_e32 v16, v16, v217
	v_mul_f32_e32 v17, v17, v217
	v_mul_f32_e32 v18, v18, v217
	v_mul_f32_e32 v19, v19, v217
	v_mul_f32_e32 v20, v20, v217
	v_mul_f32_e32 v21, v21, v217
	v_mul_f32_e32 v22, v22, v217
	v_mul_f32_e32 v23, v23, v217
	v_mul_f32_e32 v24, v24, v217
	v_mul_f32_e32 v25, v25, v217
	v_mul_f32_e32 v26, v26, v217
	v_mul_f32_e32 v27, v27, v217
	v_mul_f32_e32 v28, v28, v217
	v_mul_f32_e32 v29, v29, v217
	v_mul_f32_e32 v30, v30, v217
	v_mul_f32_e32 v31, v31, v217
	v_mul_f32_e32 v32, v32, v217
	v_mul_f32_e32 v33, v33, v217
	v_cndmask_b32_e32 v220, v220, v228, vcc
	v_cndmask_b32_e64 v221, v221, -1, vcc
	s_andn2_b64 s[26:27], s[26:27], vcc
